# v40 plus 15 and 12 VALU ops (row-sum adds, bf16 packs on surviving registers) moved from QK phase to PV phase of the attention step
# baseline (speedup 1.0000x reference)
; #define WAIT_BAR(N) asm volatile("s_waitcnt vmcnt(" #N ") lgkmcnt(0)\n\ts_barrier":::"memory")
;   #define RESC() do{ if(resc){ asm volatile("s_waitcnt lgkmcnt(0)":::"memory"); \
;       _Pragma("unroll") for(int d_=0;d_<2;++d_) _Pragma("unroll") for(int r=0;r<16;++r)o[d_][r]*=wsf[crow(r,hi)]; } }while(0)
;   #define ROT() do{sl_prev=sl_cur;sl_cur=sl_next;sl_next=(sl_next==(NSLOT-1)*SLOTB)?0:sl_next+SLOTB;}while(0)
; template<int THRL> __device__ __forceinline__ void attn_unit(const bf16*Qu,const bf16*__restrict__ Kh,const bf16*__restrict__ Vh,bf16*Ou,const int NT,const float shift,char*shm){
;     ...
;   int t=1;
;     ...
;   for(;t+5<NT;t+=2){
;     STEP(pB0,pB1,pA0,pA1,t,true,true,true);     WAIT_BAR(2); RESC(); ROT();
.LBB0_618:
	s_mov_b32 s4, s76
	s_mov_b32 s5, s26
	s_mov_b32 s25, s31
	ds_read_b64_tr_b16 v[52:53], v51 offset:24576
	ds_read_b64_tr_b16 v[54:55], v51 offset:25088
	s_waitcnt lgkmcnt(9)
	v_mfma_f32_32x32x16_bf16 v[114:129], v[190:193], v[150:153], v[34:49]
	v_add_f32_e32 v50, v82, v50
	v_add_f32_e32 v194, v83, v194
	v_add_f32_e32 v195, v84, v195
	v_add_f32_e32 v196, v85, v196
	v_add_f32_e32 v50, v86, v50
	v_add_f32_e32 v194, v87, v194
	v_cvt_pk_bf16_f32 v158, v82, v83
	v_cvt_pk_bf16_f32 v159, v84, v85
	ds_read_b64_tr_b16 v[60:61], v51 offset:28672
	ds_read_b64_tr_b16 v[62:63], v51 offset:29184
	s_waitcnt lgkmcnt(10)
	v_mfma_f32_32x32x16_bf16 v[98:113], v[186:189], v[150:153], v[34:49]
	v_add_f32_e32 v195, v88, v195
	v_add_f32_e32 v196, v89, v196
	v_add_f32_e32 v50, v90, v50
	v_add_f32_e32 v194, v91, v194
	v_cvt_pk_bf16_f32 v160, v86, v87
	v_cvt_pk_bf16_f32 v161, v88, v89
	ds_read_b64_tr_b16 v[82:83], v51 offset:25600
	ds_read_b64_tr_b16 v[84:85], v51 offset:26112
	s_waitcnt lgkmcnt(11)
	v_mfma_f32_32x32x16_bf16 v[114:129], v[182:185], v[138:141], v[114:129]
	v_add_f32_e32 v195, v92, v195
	v_add_f32_e32 v196, v93, v196
	v_cvt_pk_bf16_f32 v154, v90, v91
	v_cvt_pk_bf16_f32 v155, v92, v93
	ds_read_b64_tr_b16 v[86:87], v51 offset:29696
	ds_read_b64_tr_b16 v[88:89], v51 offset:30208
	s_waitcnt lgkmcnt(12)
	v_mfma_f32_32x32x16_bf16 v[98:113], v[178:181], v[138:141], v[98:113]
	v_add_f32_e32 v50, v66, v50
	v_add_f32_e32 v194, v67, v194
	ds_read_b64_tr_b16 v[90:91], v51 offset:26624
	ds_read_b64_tr_b16 v[92:93], v51 offset:27136
	s_waitcnt lgkmcnt(13)
	v_mfma_f32_32x32x16_bf16 v[114:129], v[174:177], v[134:137], v[114:129]
	v_add_f32_e32 v195, v68, v195
	v_add_f32_e32 v196, v69, v196
	v_add_f32_e32 v50, v70, v50
	v_add_f32_e32 v194, v71, v194
	v_cvt_pk_bf16_f32 v146, v66, v67
	v_cvt_pk_bf16_f32 v147, v68, v69
	ds_read_b64_tr_b16 v[64:65], v51 offset:30720
	ds_read_b64_tr_b16 v[66:67], v51 offset:31232
	s_waitcnt lgkmcnt(14)
	v_mfma_f32_32x32x16_bf16 v[98:113], v[170:173], v[134:137], v[98:113]
	v_add_f32_e32 v195, v72, v195
	v_add_f32_e32 v196, v73, v196
	v_add_f32_e32 v50, v74, v50
	v_add_f32_e32 v194, v75, v194
	v_cvt_pk_bf16_f32 v148, v70, v71
	v_cvt_pk_bf16_f32 v149, v72, v73
	ds_read_b64_tr_b16 v[68:69], v51 offset:27648
	ds_read_b64_tr_b16 v[70:71], v51 offset:28160
	s_waitcnt lgkmcnt(14)
	v_mfma_f32_32x32x16_bf16 v[114:129], v[166:169], v[130:133], v[114:129]
	v_cvt_pk_bf16_f32 v142, v74, v75
	ds_read_b64_tr_b16 v[72:73], v51 offset:31744
	ds_read_b64_tr_b16 v[74:75], v51 offset:32256
	v_mfma_f32_32x32x16_bf16 v[98:113], v[162:165], v[130:133], v[98:113]
	s_add_i32 s6, s31, s70
	s_mov_b32 s7, m0
	s_mov_b32 m0, s6
	s_nop 0
	global_load_lds_dwordx4 v197, s[98:99]
	s_mov_b32 m0, s7
	s_add_i32 s6, s76, s71
	s_mov_b32 s7, m0
	s_mov_b32 m0, s6
	s_nop 0
	global_load_lds_dwordx4 v197, s[100:101]
	s_mov_b32 m0, s7
	s_add_u32 s98, s98, 0x2000
	s_addc_u32 s99, s99, 0
	s_add_u32 s100, s100, 0x2000
	s_addc_u32 s101, s101, 0
	s_waitcnt lgkmcnt(14)
	v_mfma_f32_32x32x16_bf16 v[2:17], v[158:161], v[52:55], v[2:17]
	v_exp_f32_e32 v114, v114
	v_exp_f32_e32 v115, v115
	v_exp_f32_e32 v116, v116
	v_exp_f32_e32 v117, v117
	v_cvt_pk_bf16_f32 v156, v94, v95
	v_cvt_pk_bf16_f32 v157, v96, v97
	s_waitcnt lgkmcnt(12)
	v_mfma_f32_32x32x16_bf16 v[18:33], v[158:161], v[60:63], v[18:33]
	v_exp_f32_e32 v118, v118
	v_exp_f32_e32 v119, v119
	v_exp_f32_e32 v120, v120
	v_exp_f32_e32 v121, v121
	v_cvt_pk_bf16_f32 v143, v76, v77
	v_cvt_pk_bf16_f32 v144, v78, v79
	v_add_u32_e32 v52, s4, v244
	v_add_u32_e32 v198, s25, v245
	ds_read_b128 v[60:63], v52
	ds_read_b128 v[162:165], v52 offset:512
	s_waitcnt lgkmcnt(12)
	v_mfma_f32_32x32x16_bf16 v[2:17], v[154:157], v[82:85], v[2:17]
	v_exp_f32_e32 v122, v122
	v_exp_f32_e32 v123, v123
	v_exp_f32_e32 v124, v124
	v_exp_f32_e32 v125, v125
	v_cvt_pk_bf16_f32 v145, v80, v81
	v_add_f32_e32 v196, v77, v196
	ds_read_b128 v[166:169], v52 offset:2048
	ds_read_b128 v[170:173], v52 offset:2560
	s_waitcnt lgkmcnt(12)
	v_mfma_f32_32x32x16_bf16 v[18:33], v[154:157], v[86:89], v[18:33]
	v_exp_f32_e32 v126, v126
	v_exp_f32_e32 v127, v127
	v_exp_f32_e32 v128, v128
	v_exp_f32_e32 v129, v129
	v_add_f32_e32 v50, v94, v50
	v_add_f32_e32 v50, v78, v50
	ds_read_b128 v[174:177], v52 offset:4096
	ds_read_b128 v[178:181], v52 offset:4608
	s_waitcnt lgkmcnt(12)
	v_mfma_f32_32x32x16_bf16 v[2:17], v[146:149], v[90:93], v[2:17]
	v_exp_f32_e32 v98, v98
	v_exp_f32_e32 v99, v99
	v_exp_f32_e32 v100, v100
	v_exp_f32_e32 v101, v101
	v_add_f32_e32 v194, v95, v194
	v_add_f32_e32 v194, v79, v194
	ds_read_b128 v[182:185], v52 offset:6144
	ds_read_b128 v[52:55], v52 offset:6656
	s_waitcnt lgkmcnt(12)
	v_mfma_f32_32x32x16_bf16 v[18:33], v[146:149], v[64:67], v[18:33]
	v_exp_f32_e32 v102, v102
	v_exp_f32_e32 v103, v103
	v_exp_f32_e32 v104, v104
	v_exp_f32_e32 v105, v105
	v_add_f32_e32 v195, v96, v195
	v_add_f32_e32 v195, v80, v195
	s_waitcnt lgkmcnt(10)
	v_mfma_f32_32x32x16_bf16 v[2:17], v[142:145], v[68:71], v[2:17]
	v_exp_f32_e32 v106, v106
	v_exp_f32_e32 v107, v107
	v_exp_f32_e32 v108, v108
	v_exp_f32_e32 v109, v109
	v_add_f32_e32 v196, v97, v196
	v_add_f32_e32 v196, v81, v196
	s_waitcnt lgkmcnt(8)
	v_mfma_f32_32x32x16_bf16 v[18:33], v[142:145], v[72:75], v[18:33]
	v_exp_f32_e32 v110, v110
	v_exp_f32_e32 v111, v111
	v_exp_f32_e32 v112, v112
	v_exp_f32_e32 v113, v113
	v_add_f32_e32 v195, v76, v195
	s_waitcnt vmcnt(2) lgkmcnt(0)
	s_barrier
; #define WAIT_BAR(N) asm volatile("s_waitcnt vmcnt(" #N ") lgkmcnt(0)\n\ts_barrier":::"memory")
;   #define RESC() do{ if(resc){ asm volatile("s_waitcnt lgkmcnt(0)":::"memory"); \
;       _Pragma("unroll") for(int d_=0;d_<2;++d_) _Pragma("unroll") for(int r=0;r<16;++r)o[d_][r]*=wsf[crow(r,hi)]; } }while(0)
;   #define ROT() do{sl_prev=sl_cur;sl_cur=sl_next;sl_next=(sl_next==(NSLOT-1)*SLOTB)?0:sl_next+SLOTB;}while(0)
; template<int THRL> __device__ __forceinline__ void attn_unit(const bf16*Qu,const bf16*__restrict__ Kh,const bf16*__restrict__ Vh,bf16*Ou,const int NT,const float shift,char*shm){
;     ...
;   int t=1;
;     ...
;   for(;t+5<NT;t+=2){
;     STEP(pB0,pB1,pA0,pA1,t,true,true,true);     WAIT_BAR(2); RESC(); ROT();
	s_add_i32 s6, s76, 0x2000
	s_cmpk_lg_i32 s76, 0x4000
	s_cselect_b32 s31, s6, 0
	ds_read_b64_tr_b16 v[186:187], v198 offset:24576
	ds_read_b64_tr_b16 v[188:189], v198 offset:25088
	s_waitcnt lgkmcnt(9)
	v_mfma_f32_32x32x16_bf16 v[82:97], v[60:63], v[150:153], v[34:49]
	v_add_f32_e32 v50, v114, v50
	v_add_f32_e32 v194, v115, v194
	v_add_f32_e32 v195, v116, v195
	v_add_f32_e32 v196, v117, v196
	v_add_f32_e32 v50, v118, v50
	v_add_f32_e32 v194, v119, v194
	v_cvt_pk_bf16_f32 v158, v114, v115
	v_cvt_pk_bf16_f32 v159, v116, v117
	ds_read_b64_tr_b16 v[60:61], v198 offset:28672
	ds_read_b64_tr_b16 v[62:63], v198 offset:29184
	s_waitcnt lgkmcnt(10)
	v_mfma_f32_32x32x16_bf16 v[66:81], v[162:165], v[150:153], v[34:49]
	v_add_f32_e32 v195, v120, v195
	v_add_f32_e32 v196, v121, v196
	v_add_f32_e32 v50, v122, v50
	v_add_f32_e32 v194, v123, v194
	v_cvt_pk_bf16_f32 v160, v118, v119
	v_cvt_pk_bf16_f32 v161, v120, v121
	ds_read_b64_tr_b16 v[114:115], v198 offset:25600
	ds_read_b64_tr_b16 v[116:117], v198 offset:26112
	s_waitcnt lgkmcnt(11)
	v_mfma_f32_32x32x16_bf16 v[82:97], v[166:169], v[138:141], v[82:97]
	v_add_f32_e32 v195, v124, v195
	v_add_f32_e32 v196, v125, v196
	v_cvt_pk_bf16_f32 v154, v122, v123
	v_cvt_pk_bf16_f32 v155, v124, v125
	ds_read_b64_tr_b16 v[118:119], v198 offset:29696
	ds_read_b64_tr_b16 v[120:121], v198 offset:30208
	s_waitcnt lgkmcnt(12)
	v_mfma_f32_32x32x16_bf16 v[66:81], v[170:173], v[138:141], v[66:81]
	v_add_f32_e32 v50, v98, v50
	v_add_f32_e32 v194, v99, v194
	ds_read_b64_tr_b16 v[122:123], v198 offset:26624
	ds_read_b64_tr_b16 v[124:125], v198 offset:27136
	s_waitcnt lgkmcnt(13)
	v_mfma_f32_32x32x16_bf16 v[82:97], v[174:177], v[134:137], v[82:97]
	v_add_f32_e32 v195, v100, v195
	v_add_f32_e32 v196, v101, v196
	v_add_f32_e32 v50, v102, v50
	v_add_f32_e32 v194, v103, v194
	v_cvt_pk_bf16_f32 v146, v98, v99
	v_cvt_pk_bf16_f32 v147, v100, v101
	ds_read_b64_tr_b16 v[98:99], v198 offset:30720
	ds_read_b64_tr_b16 v[100:101], v198 offset:31232
	s_waitcnt lgkmcnt(14)
	v_mfma_f32_32x32x16_bf16 v[66:81], v[178:181], v[134:137], v[66:81]
	v_add_f32_e32 v195, v104, v195
	v_add_f32_e32 v196, v105, v196
	v_add_f32_e32 v50, v106, v50
	v_add_f32_e32 v194, v107, v194
	v_cvt_pk_bf16_f32 v148, v102, v103
	v_cvt_pk_bf16_f32 v149, v104, v105
	ds_read_b64_tr_b16 v[102:103], v198 offset:27648
	ds_read_b64_tr_b16 v[104:105], v198 offset:28160
	s_waitcnt lgkmcnt(14)
	v_mfma_f32_32x32x16_bf16 v[82:97], v[182:185], v[130:133], v[82:97]
	v_add_f32_e32 v195, v108, v195
	v_add_f32_e32 v196, v109, v196
	v_cvt_pk_bf16_f32 v142, v106, v107
	v_cvt_pk_bf16_f32 v143, v108, v109
	ds_read_b64_tr_b16 v[106:107], v198 offset:31744
	ds_read_b64_tr_b16 v[108:109], v198 offset:32256
	v_mfma_f32_32x32x16_bf16 v[66:81], v[52:55], v[130:133], v[66:81]
	s_add_i32 s6, s76, s70
	s_mov_b32 s7, m0
	s_mov_b32 m0, s6
	s_nop 0
	global_load_lds_dwordx4 v197, s[98:99]
	s_mov_b32 m0, s7
	s_add_i32 s6, s31, s71
	s_mov_b32 s7, m0
	s_mov_b32 m0, s6
	s_nop 0
	global_load_lds_dwordx4 v197, s[100:101]
	s_mov_b32 m0, s7
	s_add_u32 s98, s98, 0x2000
	s_addc_u32 s99, s99, 0
	s_add_u32 s100, s100, 0x2000
	s_addc_u32 s101, s101, 0
	s_waitcnt lgkmcnt(14)
	v_mfma_f32_32x32x16_bf16 v[2:17], v[158:161], v[186:189], v[2:17]
	v_exp_f32_e32 v82, v82
	v_exp_f32_e32 v83, v83
	v_exp_f32_e32 v84, v84
	v_exp_f32_e32 v85, v85
	v_cvt_pk_bf16_f32 v156, v126, v127
	v_cvt_pk_bf16_f32 v157, v128, v129
	s_waitcnt lgkmcnt(12)
	v_mfma_f32_32x32x16_bf16 v[18:33], v[158:161], v[60:63], v[18:33]
	v_exp_f32_e32 v86, v86
	v_exp_f32_e32 v87, v87
	v_exp_f32_e32 v88, v88
	v_exp_f32_e32 v89, v89
	v_cvt_pk_bf16_f32 v144, v110, v111
	v_cvt_pk_bf16_f32 v145, v112, v113
	v_add_u32_e32 v53, s31, v244
	v_add_u32_e32 v51, s76, v245
	ds_read_b128 v[190:193], v53
	ds_read_b128 v[186:189], v53 offset:512
	s_waitcnt lgkmcnt(12)
	v_mfma_f32_32x32x16_bf16 v[2:17], v[154:157], v[114:117], v[2:17]
	v_exp_f32_e32 v90, v90
	v_exp_f32_e32 v91, v91
	v_exp_f32_e32 v92, v92
	v_exp_f32_e32 v93, v93
	v_add_f32_e32 v50, v126, v50
	v_add_f32_e32 v195, v112, v195
	ds_read_b128 v[182:185], v53 offset:2048
	ds_read_b128 v[178:181], v53 offset:2560
	s_waitcnt lgkmcnt(12)
	v_mfma_f32_32x32x16_bf16 v[18:33], v[154:157], v[118:121], v[18:33]
	v_exp_f32_e32 v94, v94
	v_exp_f32_e32 v95, v95
	v_exp_f32_e32 v96, v96
	v_exp_f32_e32 v97, v97
	v_add_f32_e32 v194, v127, v194
	v_add_f32_e32 v196, v113, v196
	ds_read_b128 v[174:177], v53 offset:4096
	ds_read_b128 v[170:173], v53 offset:4608
	s_waitcnt lgkmcnt(12)
	v_mfma_f32_32x32x16_bf16 v[2:17], v[146:149], v[122:125], v[2:17]
	v_exp_f32_e32 v66, v66
	v_exp_f32_e32 v67, v67
	v_exp_f32_e32 v68, v68
	v_exp_f32_e32 v69, v69
	v_add_f32_e32 v195, v128, v195
	ds_read_b128 v[166:169], v53 offset:6144
	ds_read_b128 v[162:165], v53 offset:6656
	s_waitcnt lgkmcnt(12)
	v_mfma_f32_32x32x16_bf16 v[18:33], v[146:149], v[98:101], v[18:33]
	v_exp_f32_e32 v70, v70
	v_exp_f32_e32 v71, v71
	v_exp_f32_e32 v72, v72
	v_exp_f32_e32 v73, v73
	v_add_f32_e32 v196, v129, v196
	s_waitcnt lgkmcnt(10)
	v_mfma_f32_32x32x16_bf16 v[2:17], v[142:145], v[102:105], v[2:17]
	v_exp_f32_e32 v74, v74
	v_exp_f32_e32 v75, v75
	v_exp_f32_e32 v76, v76
	v_exp_f32_e32 v77, v77
	v_add_f32_e32 v50, v110, v50
	s_waitcnt lgkmcnt(8)
	v_mfma_f32_32x32x16_bf16 v[18:33], v[142:145], v[106:109], v[18:33]
	v_exp_f32_e32 v78, v78
	v_exp_f32_e32 v79, v79
	v_exp_f32_e32 v80, v80
	v_exp_f32_e32 v81, v81
	v_add_f32_e32 v194, v111, v194
	s_add_i32 s6, s31, 0x2000
	s_waitcnt vmcnt(2) lgkmcnt(0)
	s_barrier
	s_cmpk_lg_i32 s31, 0x4000
	s_mov_b32 s24, s76
	s_cselect_b32 s76, s6, 0
	s_add_i32 s26, s26, 2
	s_cmp_ge_i32 s26, s91
	s_cbranch_scc0 .LBB0_618
	v_add_f32_e32 v50, v50, v194
	v_add_f32_e32 v50, v50, v195
	v_add_f32_e32 v50, v50, v196
	s_add_i32 s5, s5, -3
	s_branch .LBB0_621
